# GEMM1: ALIGN_EPI barriers removed for intermediate units so the two wave-halves stay staggered through the epilogue (store bursts of the halves no longer coincide); on top of stage B
# baseline (speedup 1.0000x reference)
; #define PG8_STAGE(bufoff, gbase, voff) do { _Pragma("unroll") for (int _i = 0; _i < 2; ++_i) \
;         __builtin_amdgcn_global_load_lds((const unsigned*)((const char*)(gbase) + (voff)[_i]), (LAS unsigned*)(lds + (bufoff) + ldsw + _i * 8192), 16, 0, 0); } while (0)
; #define PG8_LDA(dst, b, h) do { _Pragma("unroll") for (int m = 0; m < 4; ++m) _Pragma("unroll") for (int k = 0; k < 2; ++k) dst[m][k] = *(const LAS bf16x8*)(lds + PG8_SA(b, h) + aoff + m * 2048 + k * 1024); } while (0)
; #define PG8_LDB(dst, b, h) do { _Pragma("unroll") for (int n = 0; n < 2; ++n) _Pragma("unroll") for (int k = 0; k < 2; ++k) dst[n][k] = *(const LAS bf16x8*)(lds + PG8_SB(b, h) + boff + n * 2048 + k * 1024); } while (0)
; #define PG8_MMA(ai, bj, At, Bt) do { __builtin_amdgcn_s_setprio(1); _Pragma("unroll") for (int m = 0; m < 4; ++m) _Pragma("unroll") for (int n = 0; n < 2; ++n) _Pragma("unroll") for (int k = 0; k < 2; ++k) \
;         acc[ai][bj][m][n] = __builtin_amdgcn_mfma_f32_16x16x32_bf16(Bt[n][k], At[m][k], acc[ai][bj][m][n], 0, 0, 0); __builtin_amdgcn_s_setprio(0); } while (0)
; #define PG8_WAIT_V(n) asm volatile("s_waitcnt vmcnt(" #n ")" ::: "memory")
; #define PG8_WAIT_L(n) asm volatile("s_waitcnt lgkmcnt(" #n ")" ::: "memory")
; #define PG8_BAR __builtin_amdgcn_s_barrier()
; template <class Epi, class Sched, bool ALIGN_EPI = false, bool SP2 = true>
; DI void gemm_phase(LAS unsigned char* lds, const Gemm g, const Sched& S, const Epi& E, f32x4 (&acc)[2][2][4][2]) {
;     ...
;         for (int t = 0; t < nt; t += 2) {
;             const bool last = (t == nt - 2);
;             const char* a1 = cA + (size_t)(t + 1) * kstep;
;             const char* a2 = last ? nA : cA + (size_t)(t + 2) * kstep; const char* b2 = last ? nB : cB + (size_t)(t + 2) * kstep;
;             const char* a3 = a2 + kstep; const char* b3 = b2 + kstep;
;             if constexpr (SP2) {
;             PG8_LDB(B0, 0, 0); PG8_LDB(B1, 0, 1); PG8_SCHED; PG8_LDA(At, 0, 0); PG8_STAGE(PG8_SA(1, 1), a1 + hstep, voffA);
;             PG8_WAIT_V(8); PG8_WAIT_L(0); PG8_BAR; PG8_MMA(0, 0, At, B0); PG8_MMA(0, 1, At, B1); PG8_BAR; PG8_SCHED;
;             PG8_LDA(At, 0, 1); PG8_STAGE(PG8_SB(0, 0), b2, voffB); PG8_STAGE(PG8_SB(0, 1), b2 + hstep, voffB); PG8_STAGE(PG8_SA(0, 0), a2, voffA);
;             PG8_WAIT_V(8); PG8_WAIT_L(0); PG8_BAR; PG8_MMA(1, 0, At, B0); PG8_MMA(1, 1, At, B1); PG8_BAR; PG8_SCHED;
.LBB0_159:
	ds_read_b128 v[150:153], v164
	ds_read_b128 v[154:157], v164 offset:1024
	ds_read_b128 v[158:161], v164 offset:2048
	ds_read_b128 v[168:171], v164 offset:3072
	ds_read_b128 v[172:175], v165
	ds_read_b128 v[180:183], v165 offset:1024
	ds_read_b128 v[184:187], v165 offset:2048
	ds_read_b128 v[188:191], v165 offset:3072
	s_add_u32 s30, s0, 0xfffc0080
	s_addc_u32 s31, s1, -1
	s_cmp_eq_u32 s62, 12
	s_cselect_b32 s35, s25, s31
	s_cselect_b32 s34, s52, s30
	s_cselect_b32 s31, s23, s55
	s_cselect_b32 s30, s53, s54
	v_lshl_add_u64 v[176:177], s[0:1], 0, v[146:147]
	s_add_i32 m0, s74, 0xc000
	ds_read_b128 v[192:195], v166
	ds_read_b128 v[196:199], v166 offset:1024
	ds_read_b128 v[202:205], v166 offset:2048
	ds_read_b128 v[206:209], v166 offset:3072
	ds_read_b128 v[210:213], v166 offset:4096
	ds_read_b128 v[214:217], v166 offset:5120
	ds_read_b128 v[218:221], v166 offset:6144
	ds_read_b128 v[222:225], v166 offset:7168
	global_load_lds_dwordx4 v[176:177], off
	v_lshl_add_u64 v[176:177], s[0:1], 0, v[148:149]
	s_add_i32 m0, s74, 0xe000
	s_nop 0
	global_load_lds_dwordx4 v[176:177], off
	s_waitcnt vmcnt(8)
	s_waitcnt lgkmcnt(0)
	s_barrier
	s_setprio 1
	s_waitcnt lgkmcnt(0)
	v_mfma_f32_16x16x32_bf16 v[124:127], v[150:153], v[192:195], v[124:127]
	v_mfma_f32_16x16x32_bf16 v[120:123], v[158:161], v[192:195], v[120:123]
	v_mfma_f32_16x16x32_bf16 v[108:111], v[150:153], v[202:205], v[108:111]
	v_mfma_f32_16x16x32_bf16 v[104:107], v[158:161], v[202:205], v[104:107]
	v_mfma_f32_16x16x32_bf16 v[92:95], v[150:153], v[210:213], v[92:95]
	v_mfma_f32_16x16x32_bf16 v[88:91], v[158:161], v[210:213], v[88:91]
	v_mfma_f32_16x16x32_bf16 v[76:79], v[150:153], v[218:221], v[76:79]
	v_mfma_f32_16x16x32_bf16 v[72:75], v[158:161], v[218:221], v[72:75]
	v_mfma_f32_16x16x32_bf16 v[124:127], v[154:157], v[196:199], v[124:127]
	v_mfma_f32_16x16x32_bf16 v[120:123], v[168:171], v[196:199], v[120:123]
	v_mfma_f32_16x16x32_bf16 v[108:111], v[154:157], v[206:209], v[108:111]
	v_mfma_f32_16x16x32_bf16 v[104:107], v[168:171], v[206:209], v[104:107]
	v_mfma_f32_16x16x32_bf16 v[92:95], v[154:157], v[214:217], v[92:95]
	v_mfma_f32_16x16x32_bf16 v[88:91], v[168:171], v[214:217], v[88:91]
	v_mfma_f32_16x16x32_bf16 v[76:79], v[154:157], v[222:225], v[76:79]
	v_mfma_f32_16x16x32_bf16 v[72:75], v[168:171], v[222:225], v[72:75]
	s_setprio 0
	s_setprio 1
	v_mfma_f32_16x16x32_bf16 v[116:119], v[172:175], v[192:195], v[116:119]
	v_mfma_f32_16x16x32_bf16 v[112:115], v[184:187], v[192:195], v[112:115]
	v_mfma_f32_16x16x32_bf16 v[100:103], v[172:175], v[202:205], v[100:103]
	v_mfma_f32_16x16x32_bf16 v[96:99], v[184:187], v[202:205], v[96:99]
	v_mfma_f32_16x16x32_bf16 v[84:87], v[172:175], v[210:213], v[84:87]
	v_mfma_f32_16x16x32_bf16 v[80:83], v[184:187], v[210:213], v[80:83]
	v_mfma_f32_16x16x32_bf16 v[68:71], v[172:175], v[218:221], v[68:71]
	v_mfma_f32_16x16x32_bf16 v[64:67], v[184:187], v[218:221], v[64:67]
	v_mfma_f32_16x16x32_bf16 v[116:119], v[180:183], v[196:199], v[116:119]
	v_mfma_f32_16x16x32_bf16 v[112:115], v[188:191], v[196:199], v[112:115]
	v_mfma_f32_16x16x32_bf16 v[100:103], v[180:183], v[206:209], v[100:103]
	v_mfma_f32_16x16x32_bf16 v[96:99], v[188:191], v[206:209], v[96:99]
	v_mfma_f32_16x16x32_bf16 v[84:87], v[180:183], v[214:217], v[84:87]
	v_mfma_f32_16x16x32_bf16 v[80:83], v[188:191], v[214:217], v[80:83]
	v_mfma_f32_16x16x32_bf16 v[68:71], v[180:183], v[222:225], v[68:71]
	v_mfma_f32_16x16x32_bf16 v[64:67], v[188:191], v[222:225], v[64:67]
	s_setprio 0
	s_barrier
	s_add_i32 s63, s82, s39
	v_lshl_add_u64 v[176:177], s[30:31], 0, v[130:131]
	s_mov_b32 m0, s63
	ds_read_b128 v[192:195], v166 offset:16384
	ds_read_b128 v[196:199], v166 offset:17408
	ds_read_b128 v[202:205], v166 offset:18432
	ds_read_b128 v[206:209], v166 offset:19456
	ds_read_b128 v[210:213], v166 offset:20480
	ds_read_b128 v[214:217], v166 offset:21504
	ds_read_b128 v[218:221], v166 offset:22528
	ds_read_b128 v[222:225], v166 offset:23552
	global_load_lds_dwordx4 v[176:177], off
	s_add_i32 m0, s63, 0x2000
	s_add_u32 s72, s30, 0x10000
	v_lshl_add_u64 v[226:227], s[30:31], 0, v[134:135]
	s_addc_u32 s73, s31, 0
	s_add_i32 s63, s83, s39
	global_load_lds_dwordx4 v[226:227], off
	v_lshl_add_u64 v[228:229], s[72:73], 0, v[130:131]
	s_mov_b32 m0, s63
	v_lshl_add_u64 v[230:231], s[34:35], 0, v[132:133]
	global_load_lds_dwordx4 v[228:229], off
	v_lshl_add_u64 v[228:229], s[72:73], 0, v[134:135]
	s_add_i32 m0, s63, 0x2000
	s_nop 0
	global_load_lds_dwordx4 v[228:229], off
	v_lshl_add_u64 v[228:229], s[34:35], 0, v[128:129]
	s_mov_b32 m0, s74
	s_nop 0
	global_load_lds_dwordx4 v[228:229], off
	s_mov_b32 m0, s75
	s_nop 0
	global_load_lds_dwordx4 v[230:231], off
	s_waitcnt vmcnt(8)
	s_waitcnt lgkmcnt(0)
	s_barrier
; #define PG8_STAGE(bufoff, gbase, voff) do { _Pragma("unroll") for (int _i = 0; _i < 2; ++_i) \
;         __builtin_amdgcn_global_load_lds((const unsigned*)((const char*)(gbase) + (voff)[_i]), (LAS unsigned*)(lds + (bufoff) + ldsw + _i * 8192), 16, 0, 0); } while (0)
; #define PG8_LDA(dst, b, h) do { _Pragma("unroll") for (int m = 0; m < 4; ++m) _Pragma("unroll") for (int k = 0; k < 2; ++k) dst[m][k] = *(const LAS bf16x8*)(lds + PG8_SA(b, h) + aoff + m * 2048 + k * 1024); } while (0)
; #define PG8_LDB(dst, b, h) do { _Pragma("unroll") for (int n = 0; n < 2; ++n) _Pragma("unroll") for (int k = 0; k < 2; ++k) dst[n][k] = *(const LAS bf16x8*)(lds + PG8_SB(b, h) + boff + n * 2048 + k * 1024); } while (0)
; #define PG8_MMA(ai, bj, At, Bt) do { __builtin_amdgcn_s_setprio(1); _Pragma("unroll") for (int m = 0; m < 4; ++m) _Pragma("unroll") for (int n = 0; n < 2; ++n) _Pragma("unroll") for (int k = 0; k < 2; ++k) \
;         acc[ai][bj][m][n] = __builtin_amdgcn_mfma_f32_16x16x32_bf16(Bt[n][k], At[m][k], acc[ai][bj][m][n], 0, 0, 0); __builtin_amdgcn_s_setprio(0); } while (0)
; #define PG8_WAIT_V(n) asm volatile("s_waitcnt vmcnt(" #n ")" ::: "memory")
; #define PG8_WAIT_L(n) asm volatile("s_waitcnt lgkmcnt(" #n ")" ::: "memory")
; #define PG8_BAR __builtin_amdgcn_s_barrier()
; #define PG8_SCHED __builtin_amdgcn_sched_barrier(0)
; template <class Epi, class Sched, bool ALIGN_EPI = false, bool SP2 = true>
; DI void gemm_phase(LAS unsigned char* lds, const Gemm g, const Sched& S, const Epi& E, f32x4 (&acc)[2][2][4][2]) {
;     ...
;             PG8_WAIT_V(8); PG8_WAIT_L(0); PG8_BAR; PG8_MMA(1, 0, At, B0); PG8_MMA(1, 1, At, B1); PG8_BAR; PG8_SCHED;
;             PG8_LDB(B0, 1, 0); PG8_LDB(B1, 1, 1); PG8_SCHED; PG8_LDA(At, 1, 0); PG8_STAGE(PG8_SA(0, 1), a2 + hstep, voffA);
;             PG8_WAIT_V(8); PG8_WAIT_L(0); PG8_BAR; PG8_MMA(0, 0, At, B0); PG8_MMA(0, 1, At, B1); PG8_BAR; PG8_SCHED;
	s_setprio 1
	s_waitcnt lgkmcnt(0)
	v_mfma_f32_16x16x32_bf16 v[60:63], v[150:153], v[192:195], v[60:63]
	v_mfma_f32_16x16x32_bf16 v[56:59], v[158:161], v[192:195], v[56:59]
	v_mfma_f32_16x16x32_bf16 v[44:47], v[150:153], v[202:205], v[44:47]
	v_mfma_f32_16x16x32_bf16 v[40:43], v[158:161], v[202:205], v[40:43]
	v_mfma_f32_16x16x32_bf16 v[28:31], v[150:153], v[210:213], v[28:31]
	v_mfma_f32_16x16x32_bf16 v[24:27], v[158:161], v[210:213], v[24:27]
	v_mfma_f32_16x16x32_bf16 v[12:15], v[150:153], v[218:221], v[12:15]
	v_mfma_f32_16x16x32_bf16 v[8:11], v[158:161], v[218:221], v[8:11]
	v_mfma_f32_16x16x32_bf16 v[60:63], v[154:157], v[196:199], v[60:63]
	v_mfma_f32_16x16x32_bf16 v[56:59], v[168:171], v[196:199], v[56:59]
	v_mfma_f32_16x16x32_bf16 v[44:47], v[154:157], v[206:209], v[44:47]
	v_mfma_f32_16x16x32_bf16 v[40:43], v[168:171], v[206:209], v[40:43]
	v_mfma_f32_16x16x32_bf16 v[28:31], v[154:157], v[214:217], v[28:31]
	v_mfma_f32_16x16x32_bf16 v[24:27], v[168:171], v[214:217], v[24:27]
	v_mfma_f32_16x16x32_bf16 v[12:15], v[154:157], v[222:225], v[12:15]
	v_mfma_f32_16x16x32_bf16 v[8:11], v[168:171], v[222:225], v[8:11]
	s_setprio 0
	s_setprio 1
	v_mfma_f32_16x16x32_bf16 v[52:55], v[172:175], v[192:195], v[52:55]
	v_mfma_f32_16x16x32_bf16 v[48:51], v[184:187], v[192:195], v[48:51]
	v_mfma_f32_16x16x32_bf16 v[36:39], v[172:175], v[202:205], v[36:39]
	v_mfma_f32_16x16x32_bf16 v[32:35], v[184:187], v[202:205], v[32:35]
	v_mfma_f32_16x16x32_bf16 v[20:23], v[172:175], v[210:213], v[20:23]
	v_mfma_f32_16x16x32_bf16 v[16:19], v[184:187], v[210:213], v[16:19]
	v_mfma_f32_16x16x32_bf16 v[4:7], v[172:175], v[218:221], v[4:7]
	v_mfma_f32_16x16x32_bf16 v[0:3], v[184:187], v[218:221], v[0:3]
	v_mfma_f32_16x16x32_bf16 v[52:55], v[180:183], v[196:199], v[52:55]
	v_mfma_f32_16x16x32_bf16 v[48:51], v[188:191], v[196:199], v[48:51]
	v_mfma_f32_16x16x32_bf16 v[36:39], v[180:183], v[206:209], v[36:39]
	v_mfma_f32_16x16x32_bf16 v[32:35], v[188:191], v[206:209], v[32:35]
	v_mfma_f32_16x16x32_bf16 v[20:23], v[180:183], v[214:217], v[20:23]
	v_mfma_f32_16x16x32_bf16 v[16:19], v[188:191], v[214:217], v[16:19]
	v_mfma_f32_16x16x32_bf16 v[4:7], v[180:183], v[222:225], v[4:7]
	v_mfma_f32_16x16x32_bf16 v[0:3], v[188:191], v[222:225], v[0:3]
	s_setprio 0
	s_barrier
	s_add_i32 s63, 0, 0x18000
	s_add_i32 s64, 0, 0x1c000
	v_add_u32_e32 v168, s63, v143
	v_add_u32_e32 v178, s64, v143
	ds_read_b128 v[150:153], v168
	ds_read_b128 v[154:157], v168 offset:1024
	ds_read_b128 v[158:161], v168 offset:2048
	ds_read_b128 v[168:171], v168 offset:3072
	ds_read_b128 v[172:175], v178
	ds_read_b128 v[180:183], v178 offset:1024
	ds_read_b128 v[184:187], v178 offset:2048
	ds_read_b128 v[188:191], v178 offset:3072
	s_add_u32 s34, s34, 0x40000
	s_addc_u32 s35, s35, 0
	s_mov_b32 m0, s76
	v_lshl_add_u64 v[232:233], s[34:35], 0, v[128:129]
	ds_read_b128 v[192:195], v166 offset:32768
	ds_read_b128 v[196:199], v166 offset:33792
	ds_read_b128 v[202:205], v166 offset:34816
	ds_read_b128 v[206:209], v166 offset:35840
	ds_read_b128 v[210:213], v166 offset:36864
	ds_read_b128 v[214:217], v166 offset:37888
	ds_read_b128 v[218:221], v166 offset:38912
	ds_read_b128 v[222:225], v166 offset:39936
	global_load_lds_dwordx4 v[232:233], off
	v_lshl_add_u64 v[232:233], s[34:35], 0, v[132:133]
	s_mov_b32 m0, s77
	s_nop 0
	global_load_lds_dwordx4 v[232:233], off
	s_waitcnt vmcnt(8)
	s_waitcnt lgkmcnt(0)
	s_barrier
	s_setprio 1
	s_waitcnt lgkmcnt(0)
	v_mfma_f32_16x16x32_bf16 v[124:127], v[150:153], v[192:195], v[124:127]
	v_mfma_f32_16x16x32_bf16 v[120:123], v[158:161], v[192:195], v[120:123]
	v_mfma_f32_16x16x32_bf16 v[108:111], v[150:153], v[202:205], v[108:111]
	v_mfma_f32_16x16x32_bf16 v[104:107], v[158:161], v[202:205], v[104:107]
	v_mfma_f32_16x16x32_bf16 v[92:95], v[150:153], v[210:213], v[92:95]
	v_mfma_f32_16x16x32_bf16 v[88:91], v[158:161], v[210:213], v[88:91]
	v_mfma_f32_16x16x32_bf16 v[76:79], v[150:153], v[218:221], v[76:79]
	v_mfma_f32_16x16x32_bf16 v[72:75], v[158:161], v[218:221], v[72:75]
	v_mfma_f32_16x16x32_bf16 v[124:127], v[154:157], v[196:199], v[124:127]
	v_mfma_f32_16x16x32_bf16 v[120:123], v[168:171], v[196:199], v[120:123]
	v_mfma_f32_16x16x32_bf16 v[108:111], v[154:157], v[206:209], v[108:111]
	v_mfma_f32_16x16x32_bf16 v[104:107], v[168:171], v[206:209], v[104:107]
	v_mfma_f32_16x16x32_bf16 v[92:95], v[154:157], v[214:217], v[92:95]
	v_mfma_f32_16x16x32_bf16 v[88:91], v[168:171], v[214:217], v[88:91]
	v_mfma_f32_16x16x32_bf16 v[76:79], v[154:157], v[222:225], v[76:79]
	v_mfma_f32_16x16x32_bf16 v[72:75], v[168:171], v[222:225], v[72:75]
	s_setprio 0
	s_setprio 1
	v_mfma_f32_16x16x32_bf16 v[116:119], v[172:175], v[192:195], v[116:119]
	v_mfma_f32_16x16x32_bf16 v[112:115], v[184:187], v[192:195], v[112:115]
	v_mfma_f32_16x16x32_bf16 v[100:103], v[172:175], v[202:205], v[100:103]
	v_mfma_f32_16x16x32_bf16 v[96:99], v[184:187], v[202:205], v[96:99]
	v_mfma_f32_16x16x32_bf16 v[84:87], v[172:175], v[210:213], v[84:87]
	v_mfma_f32_16x16x32_bf16 v[80:83], v[184:187], v[210:213], v[80:83]
	v_mfma_f32_16x16x32_bf16 v[68:71], v[172:175], v[218:221], v[68:71]
	v_mfma_f32_16x16x32_bf16 v[64:67], v[184:187], v[218:221], v[64:67]
	v_mfma_f32_16x16x32_bf16 v[116:119], v[180:183], v[196:199], v[116:119]
	v_mfma_f32_16x16x32_bf16 v[112:115], v[188:191], v[196:199], v[112:115]
	v_mfma_f32_16x16x32_bf16 v[100:103], v[180:183], v[206:209], v[100:103]
	v_mfma_f32_16x16x32_bf16 v[96:99], v[188:191], v[206:209], v[96:99]
	v_mfma_f32_16x16x32_bf16 v[84:87], v[180:183], v[214:217], v[84:87]
	v_mfma_f32_16x16x32_bf16 v[80:83], v[188:191], v[214:217], v[80:83]
	v_mfma_f32_16x16x32_bf16 v[68:71], v[180:183], v[222:225], v[68:71]
	v_mfma_f32_16x16x32_bf16 v[64:67], v[188:191], v[222:225], v[64:67]
	s_setprio 0
	s_barrier
; #define PG8_STAGE(bufoff, gbase, voff) do { _Pragma("unroll") for (int _i = 0; _i < 2; ++_i) \
;         __builtin_amdgcn_global_load_lds((const unsigned*)((const char*)(gbase) + (voff)[_i]), (LAS unsigned*)(lds + (bufoff) + ldsw + _i * 8192), 16, 0, 0); } while (0)
; #define PG8_LDA(dst, b, h) do { _Pragma("unroll") for (int m = 0; m < 4; ++m) _Pragma("unroll") for (int k = 0; k < 2; ++k) dst[m][k] = *(const LAS bf16x8*)(lds + PG8_SA(b, h) + aoff + m * 2048 + k * 1024); } while (0)
; #define PG8_MMA(ai, bj, At, Bt) do { __builtin_amdgcn_s_setprio(1); _Pragma("unroll") for (int m = 0; m < 4; ++m) _Pragma("unroll") for (int n = 0; n < 2; ++n) _Pragma("unroll") for (int k = 0; k < 2; ++k) \
;         acc[ai][bj][m][n] = __builtin_amdgcn_mfma_f32_16x16x32_bf16(Bt[n][k], At[m][k], acc[ai][bj][m][n], 0, 0, 0); __builtin_amdgcn_s_setprio(0); } while (0)
; #define PG8_WAIT_V(n) asm volatile("s_waitcnt vmcnt(" #n ")" ::: "memory")
; #define PG8_WAIT_L(n) asm volatile("s_waitcnt lgkmcnt(" #n ")" ::: "memory")
; #define PG8_BAR __builtin_amdgcn_s_barrier()
; #define PG8_SCHED __builtin_amdgcn_sched_barrier(0)
; template <class Epi, class Sched, bool ALIGN_EPI = false, bool SP2 = true>
; DI void gemm_phase(LAS unsigned char* lds, const Gemm g, const Sched& S, const Epi& E, f32x4 (&acc)[2][2][4][2]) {
;     ...
;             PG8_LDA(At, 1, 1); PG8_STAGE(PG8_SB(1, 0), b3, voffB); PG8_STAGE(PG8_SB(1, 1), b3 + hstep, voffB); PG8_STAGE(PG8_SA(1, 0), a3, voffA);
;             PG8_WAIT_V(8); PG8_WAIT_L(0); PG8_BAR; PG8_MMA(1, 0, At, B0); PG8_MMA(1, 1, At, B1); PG8_BAR; PG8_SCHED;
;     ...
;         if constexpr (ALIGN_EPI) { if (wr == 0) PG8_BAR; }
	s_add_i32 s34, s63, s39
	v_lshl_add_u64 v[176:177], v[176:177], 0, s[14:15]
	s_mov_b32 m0, s34
	ds_read_b128 v[192:195], v166 offset:49152
	ds_read_b128 v[196:199], v166 offset:50176
	ds_read_b128 v[202:205], v166 offset:51200
	ds_read_b128 v[206:209], v166 offset:52224
	ds_read_b128 v[210:213], v166 offset:53248
	ds_read_b128 v[214:217], v166 offset:54272
	ds_read_b128 v[218:221], v166 offset:55296
	ds_read_b128 v[222:225], v166 offset:56320
	global_load_lds_dwordx4 v[176:177], off
	s_add_i32 m0, s34, 0x2000
	s_add_u32 s30, s30, 0x10080
	v_lshl_add_u64 v[176:177], v[226:227], 0, s[14:15]
	s_addc_u32 s31, s31, 0
	s_add_i32 s34, s64, s39
	global_load_lds_dwordx4 v[176:177], off
	v_lshl_add_u64 v[176:177], s[30:31], 0, v[130:131]
	s_mov_b32 m0, s34
	s_nop 0
	global_load_lds_dwordx4 v[176:177], off
	v_lshl_add_u64 v[176:177], s[30:31], 0, v[134:135]
	s_add_i32 m0, s34, 0x2000
	s_nop 0
	global_load_lds_dwordx4 v[176:177], off
	v_lshl_add_u64 v[176:177], v[228:229], 0, s[14:15]
	s_mov_b32 m0, s80
	s_nop 0
	global_load_lds_dwordx4 v[176:177], off
	v_lshl_add_u64 v[176:177], v[230:231], 0, s[14:15]
	s_mov_b32 m0, s81
	s_nop 0
	global_load_lds_dwordx4 v[176:177], off
	s_waitcnt vmcnt(8)
	s_waitcnt lgkmcnt(0)
	s_barrier
	s_setprio 1
	s_waitcnt lgkmcnt(0)
	v_mfma_f32_16x16x32_bf16 v[60:63], v[150:153], v[192:195], v[60:63]
	v_mfma_f32_16x16x32_bf16 v[56:59], v[158:161], v[192:195], v[56:59]
	v_mfma_f32_16x16x32_bf16 v[44:47], v[150:153], v[202:205], v[44:47]
	v_mfma_f32_16x16x32_bf16 v[40:43], v[158:161], v[202:205], v[40:43]
	v_mfma_f32_16x16x32_bf16 v[28:31], v[150:153], v[210:213], v[28:31]
	v_mfma_f32_16x16x32_bf16 v[24:27], v[158:161], v[210:213], v[24:27]
	v_mfma_f32_16x16x32_bf16 v[12:15], v[150:153], v[218:221], v[12:15]
	v_mfma_f32_16x16x32_bf16 v[8:11], v[158:161], v[218:221], v[8:11]
	v_mfma_f32_16x16x32_bf16 v[60:63], v[154:157], v[196:199], v[60:63]
	v_mfma_f32_16x16x32_bf16 v[56:59], v[168:171], v[196:199], v[56:59]
	v_mfma_f32_16x16x32_bf16 v[44:47], v[154:157], v[206:209], v[44:47]
	v_mfma_f32_16x16x32_bf16 v[40:43], v[168:171], v[206:209], v[40:43]
	v_mfma_f32_16x16x32_bf16 v[28:31], v[154:157], v[214:217], v[28:31]
	v_mfma_f32_16x16x32_bf16 v[24:27], v[168:171], v[214:217], v[24:27]
	v_mfma_f32_16x16x32_bf16 v[12:15], v[154:157], v[222:225], v[12:15]
	v_mfma_f32_16x16x32_bf16 v[8:11], v[168:171], v[222:225], v[8:11]
	s_setprio 0
	s_setprio 1
	v_mfma_f32_16x16x32_bf16 v[52:55], v[172:175], v[192:195], v[52:55]
	v_mfma_f32_16x16x32_bf16 v[48:51], v[184:187], v[192:195], v[48:51]
	v_mfma_f32_16x16x32_bf16 v[36:39], v[172:175], v[202:205], v[36:39]
	v_mfma_f32_16x16x32_bf16 v[32:35], v[184:187], v[202:205], v[32:35]
	v_mfma_f32_16x16x32_bf16 v[20:23], v[172:175], v[210:213], v[20:23]
	v_mfma_f32_16x16x32_bf16 v[16:19], v[184:187], v[210:213], v[16:19]
	v_mfma_f32_16x16x32_bf16 v[4:7], v[172:175], v[218:221], v[4:7]
	v_mfma_f32_16x16x32_bf16 v[0:3], v[184:187], v[218:221], v[0:3]
	v_mfma_f32_16x16x32_bf16 v[52:55], v[180:183], v[196:199], v[52:55]
	v_mfma_f32_16x16x32_bf16 v[48:51], v[188:191], v[196:199], v[48:51]
	v_mfma_f32_16x16x32_bf16 v[36:39], v[180:183], v[206:209], v[36:39]
	v_mfma_f32_16x16x32_bf16 v[32:35], v[188:191], v[206:209], v[32:35]
	v_mfma_f32_16x16x32_bf16 v[20:23], v[180:183], v[214:217], v[20:23]
	v_mfma_f32_16x16x32_bf16 v[16:19], v[188:191], v[214:217], v[16:19]
	v_mfma_f32_16x16x32_bf16 v[4:7], v[180:183], v[222:225], v[4:7]
	v_mfma_f32_16x16x32_bf16 v[0:3], v[188:191], v[222:225], v[0:3]
	s_setprio 0
	s_barrier
	s_add_i32 s62, s62, 2
	s_add_u32 s0, s0, 0x100
	s_addc_u32 s1, s1, 0
	s_add_u32 s54, s54, 0x100
	s_addc_u32 s55, s55, 0
	s_cmp_gt_u32 s62, 13
	s_cbranch_scc0 .LBB0_159
	s_cmp_lg_u64 s[20:21], 0
	s_cbranch_scc1 .LBB0_162
	s_and_b64 vcc, exec, s[16:17]
	s_cbranch_vccz .LBB0_162
	s_barrier

; #define PG8_BAR __builtin_amdgcn_s_barrier()
; template <class Epi, class Sched, bool ALIGN_EPI = false, bool SP2 = true>
; DI void gemm_phase(LAS unsigned char* lds, const Gemm g, const Sched& S, const Epi& E, f32x4 (&acc)[2][2][4][2]) {
;     ...
;         cur = nxt; cA = nA; cB = nB; ++ui;
;         if constexpr (ALIGN_EPI) { if (wr == 1) PG8_BAR; }
.Lk2d_7:
	s_cbranch_vccnz .LBB0_142
	s_andn2_b64 vcc, exec, s[12:13]
	s_cbranch_vccnz .LBB0_141
	s_branch .LBB0_141
